# attention A prologue: K(1) tile load issued together with Q/K0/V0 into the free V staging registers
# speedup vs baseline: 1.0170x; 1.0015x over previous
.LBB0_768:
	s_lshl_b32 s20, s31, 1
	s_bfe_u32 s27, s31, 0x10005
	s_lshl_b32 s5, s31, 6
	s_and_b32 s20, s20, 2
	s_and_b32 s41, s5, 0x780
	s_lshl_b32 s5, s27, 2
	s_add_i32 s20, s20, s33
	s_add_i32 s26, s20, s5
	s_add_i32 s20, s41, 0xffffff80
	s_ashr_i32 s4, s31, 6
	s_ashr_i32 s50, s20, 6
	s_add_i32 s20, s41, 0xff
	s_ashr_i32 s5, s4, 31
	s_lshr_b32 s20, s20, 6
	s_max_i32 s42, s50, 0
	s_min_u32 s43, s20, 31
	s_lshl_b64 s[20:21], s[4:5], 21
	s_add_u32 s20, s34, s20
	s_addc_u32 s21, s35, s21
	s_lshl_b32 s22, s26, 6
	s_ashr_i32 s23, s22, 31
	s_lshl_b64 s[24:25], s[22:23], 1
	s_add_u32 s44, s20, s24
	s_addc_u32 s45, s21, s25
	s_lshl_b64 s[24:25], s[4:5], 19
	s_add_u32 s4, s36, s24
	s_addc_u32 s5, s37, s25
	s_lshl_b32 s27, s27, 7
	s_add_u32 s4, s4, s27
	s_addc_u32 s5, s5, 0
	s_add_u32 s48, s38, s24
	s_addc_u32 s49, s39, s25
	s_add_u32 s48, s48, s27
	s_addc_u32 s49, s49, 0
	s_ashr_i32 s27, s26, 31
	v_or_b32_e32 v190, s41, v178
	s_lshl_b64 s[26:27], s[26:27], 2
	v_lshlrev_b32_e32 v0, 10, v190
	s_add_u32 s26, s8, s26
	v_lshl_add_u64 v[2:3], s[44:45], 0, v[0:1]
	s_addc_u32 s27, s9, s27
	v_lshl_add_u64 v[2:3], v[2:3], 0, v[164:165]
	s_lshl_b32 s44, s42, 6
	global_load_dwordx4 v[130:133], v[2:3], off
	global_load_dwordx4 v[134:137], v[2:3], off offset:32
	global_load_dwordx4 v[138:141], v[2:3], off offset:64
	global_load_dwordx4 v[142:145], v[2:3], off offset:96
	v_add_u32_e32 v2, s44, v179
	v_ashrrev_i32_e32 v3, 31, v2
	v_lshlrev_b64 v[2:3], 8, v[2:3]
	v_lshl_add_u64 v[4:5], s[4:5], 0, v[2:3]
	v_lshl_add_u64 v[6:7], s[48:49], 0, v[2:3]
	v_lshl_add_u64 v[4:5], v[4:5], 0, v[156:157]
	v_lshl_add_u64 v[6:7], v[6:7], 0, v[156:157]
	global_load_dwordx4 v[146:149], v[4:5], off
	s_nop 0
	global_load_dwordx4 v[4:7], v[6:7], off
	s_nop 0
	global_load_dword v0, v1, s[26:27]
	s_cmp_lt_i32 s50, s43
	s_cselect_b64 s[26:27], -1, 0
	s_cmp_ge_i32 s50, s43
	s_cbranch_scc1 .Lk1pre_1
	v_add_u32_e32 v150, s44, v180
	v_ashrrev_i32_e32 v151, 31, v150
	v_lshlrev_b64 v[150:151], 8, v[150:151]
	v_lshl_add_u64 v[150:151], s[4:5], 0, v[150:151]
	v_lshl_add_u64 v[150:151], v[154:155], 1, v[150:151]
	global_load_dwordx4 v[150:153], v[150:151], off
.Lk1pre_1:
	s_waitcnt vmcnt(2)
	ds_write_b128 v186, v[146:149]
	s_waitcnt vmcnt(1)
	ds_write_b128 v187, v[4:7] offset:18432
.LBB0_770:
	s_waitcnt lgkmcnt(0)
	s_barrier
	ds_read_b128 v[4:7], v189
	ds_read_b128 v[8:11], v189 offset:32
	s_waitcnt lgkmcnt(1)
	v_mfma_f32_32x32x16_bf16 v[34:49], v[4:7], v[130:133], 0
	ds_read_b128 v[4:7], v189 offset:4608
	ds_read_b128 v[12:15], v189 offset:4640
	s_andn2_b64 vcc, exec, s[26:27]
	s_waitcnt lgkmcnt(1)
	v_mfma_f32_32x32x16_bf16 v[50:65], v[4:7], v[130:133], 0
	v_mfma_f32_32x32x16_bf16 v[34:49], v[8:11], v[134:137], v[34:49]
	ds_read_b128 v[4:7], v189 offset:64
	ds_read_b128 v[8:11], v189 offset:96
	s_waitcnt lgkmcnt(2)
	v_mfma_f32_32x32x16_bf16 v[50:65], v[12:15], v[134:137], v[50:65]
	s_waitcnt lgkmcnt(1)
	v_mfma_f32_32x32x16_bf16 v[34:49], v[4:7], v[138:141], v[34:49]
	ds_read_b128 v[4:7], v189 offset:4672
	ds_read_b128 v[12:15], v189 offset:4704
	s_waitcnt lgkmcnt(1)
	v_mfma_f32_32x32x16_bf16 v[50:65], v[4:7], v[138:141], v[50:65]
	v_cndmask_b32_e64 v4, 0, 1, s[26:27]
	v_cmp_ne_u32_e64 s[4:5], 1, v4
	v_mfma_f32_32x32x16_bf16 v[34:49], v[8:11], v[142:145], v[34:49]
	s_waitcnt lgkmcnt(0)
	v_mfma_f32_32x32x16_bf16 v[50:65], v[12:15], v[142:145], v[50:65]
	s_cbranch_vccnz .LBB0_772
	s_waitcnt vmcnt(0)
	ds_write_b128 v188, v[150:153] offset:9216

.LBB0_2828:
	s_lshl_b32 s20, s31, 1
	s_bfe_u32 s27, s31, 0x10005
	s_lshl_b32 s5, s31, 6
	s_and_b32 s20, s20, 2
	s_and_b32 s41, s5, 0x780
	s_lshl_b32 s5, s27, 2
	s_add_i32 s20, s20, s33
	s_add_i32 s26, s20, s5
	s_add_i32 s20, s41, 0xffffff80
	s_ashr_i32 s4, s31, 6
	s_ashr_i32 s50, s20, 6
	s_add_i32 s20, s41, 0xff
	s_ashr_i32 s5, s4, 31
	s_lshr_b32 s20, s20, 6
	s_max_i32 s42, s50, 0
	s_min_u32 s43, s20, 31
	s_lshl_b64 s[20:21], s[4:5], 21
	s_add_u32 s20, s34, s20
	s_addc_u32 s21, s35, s21
	s_lshl_b32 s22, s26, 6
	s_ashr_i32 s23, s22, 31
	s_lshl_b64 s[24:25], s[22:23], 1
	s_add_u32 s44, s20, s24
	s_addc_u32 s45, s21, s25
	s_lshl_b64 s[24:25], s[4:5], 19
	s_add_u32 s4, s36, s24
	s_addc_u32 s5, s37, s25
	s_lshl_b32 s27, s27, 7
	s_add_u32 s4, s4, s27
	s_addc_u32 s5, s5, 0
	s_add_u32 s48, s38, s24
	s_addc_u32 s49, s39, s25
	s_add_u32 s48, s48, s27
	s_addc_u32 s49, s49, 0
	s_ashr_i32 s27, s26, 31
	v_or_b32_e32 v190, s41, v178
	s_lshl_b64 s[26:27], s[26:27], 2
	v_lshlrev_b32_e32 v0, 10, v190
	s_add_u32 s26, s8, s26
	v_lshl_add_u64 v[2:3], s[44:45], 0, v[0:1]
	s_addc_u32 s27, s9, s27
	v_lshl_add_u64 v[2:3], v[2:3], 0, v[164:165]
	s_lshl_b32 s44, s42, 6
	global_load_dwordx4 v[130:133], v[2:3], off
	global_load_dwordx4 v[134:137], v[2:3], off offset:32
	global_load_dwordx4 v[138:141], v[2:3], off offset:64
	global_load_dwordx4 v[142:145], v[2:3], off offset:96
	v_add_u32_e32 v2, s44, v179
	v_ashrrev_i32_e32 v3, 31, v2
	v_lshlrev_b64 v[2:3], 8, v[2:3]
	v_lshl_add_u64 v[4:5], s[4:5], 0, v[2:3]
	v_lshl_add_u64 v[6:7], s[48:49], 0, v[2:3]
	v_lshl_add_u64 v[4:5], v[4:5], 0, v[156:157]
	v_lshl_add_u64 v[6:7], v[6:7], 0, v[156:157]
	global_load_dwordx4 v[146:149], v[4:5], off
	s_nop 0
	global_load_dwordx4 v[4:7], v[6:7], off
	s_nop 0
	global_load_dword v0, v1, s[26:27] offset:32
	s_cmp_lt_i32 s50, s43
	s_cselect_b64 s[26:27], -1, 0
	s_cmp_ge_i32 s50, s43
	s_cbranch_scc1 .Lk1pre_0
	v_add_u32_e32 v150, s44, v180
	v_ashrrev_i32_e32 v151, 31, v150
	v_lshlrev_b64 v[150:151], 8, v[150:151]
	v_lshl_add_u64 v[150:151], s[4:5], 0, v[150:151]
	v_lshl_add_u64 v[150:151], v[154:155], 1, v[150:151]
	global_load_dwordx4 v[150:153], v[150:151], off
